# stick-breaking prompt units queued per XCD: all units of a (b, h) run on one XCD so its L2 holds that head's K/V tiles
# baseline (speedup 1.0000x reference)
; #define LAS __attribute__((address_space(3)))
; __device__ __forceinline__ void p3_scan_and_sb(const Params& P, float* lds) {
;     ...
;         {
;             volatile LAS unsigned* qw = gctl + 4 + grp;
;             unsigned* qhead = (unsigned*)(P.ws + WS_BAR) + QW_SB;
;             const bool popper = (gw == 0 && lane == 0);
;             unsigned nxt = 0u;
;             if (popper) nxt = atomicAdd(qhead, 1u);
;             for (;;) {
;                 if (popper) qw[0] = nxt;
;                 sba::bar4(G, lane);
;                 const unsigned u = qw[0];
;                 sba::bar4(G, lane);
;                 if (u >= 768u) break;
;                 if (popper) nxt = atomicAdd(qhead, 1u);
;                 const int qb = 31 - (int)(u / 24u), bh = (int)(u % 24u);
.LBB0_1092:
	v_readlane_b32 s0, v252, 60
	v_readlane_b32 s1, v252, 61
	s_or_b64 exec, exec, s[0:1]
	v_bfe_u32 v2, v0, 6, 2
	v_readlane_b32 s2, v252, 53
	s_nop 1
	s_and_b32 s2, s2, 7
	s_mul_i32 s100, s2, 3
	s_mul_i32 s2, s2, 28
	s_add_u32 s0, s78, 0x3800
	s_addc_u32 s1, s79, 0
	s_add_u32 s0, s0, s2
	s_addc_u32 s1, s1, 0
	v_or_b32_e32 v3, v2, v1
	v_writelane_b32 v252, s0, 60
	v_mov_b32_e32 v153, 0
	v_cmp_eq_u32_e32 vcc, 0, v3
	v_writelane_b32 v252, s1, 61
	s_and_saveexec_b64 s[0:1], vcc
	s_cbranch_execz .LBB0_1096
	s_mov_b64 s[6:7], exec
	v_mbcnt_lo_u32_b32 v3, s6, 0
	v_mbcnt_hi_u32_b32 v3, s7, v3
	v_cmp_eq_u32_e64 s[4:5], 0, v3
	s_and_saveexec_b64 s[2:3], s[4:5]
	s_cbranch_execz .LBB0_1095
	s_bcnt1_i32_b64 s4, s[6:7]
	v_mov_b32_e32 v5, s4
	v_readlane_b32 s4, v252, 60
	v_mov_b32_e32 v4, 0
	v_readlane_b32 s5, v252, 61
	s_nop 4
	global_atomic_add v4, v4, v5, s[4:5] sc0
.LBB0_1095:
	s_or_b64 exec, exec, s[2:3]
	s_waitcnt vmcnt(0)
	v_readfirstlane_b32 s2, v4
	s_nop 1
	v_add_u32_e32 v153, s2, v3
	v_mul_u32_u24_e32 v4, 0xaaab, v153
	v_lshrrev_b32_e32 v4, 17, v4
	v_mul_u32_u24_e32 v5, 3, v4
	v_sub_u32_e32 v5, v153, v5
	v_mul_u32_u24_e32 v4, 24, v4
	v_add3_u32 v153, v4, v5, s100

; __device__ __forceinline__ void p3_scan_and_sb(const Params& P, float* lds) {
;     ...
;                 if (popper) nxt = atomicAdd(qhead, 1u);
;                 const int qb = 31 - (int)(u / 24u), bh = (int)(u % 24u);
.LBB0_1133:
	s_or_b64 exec, exec, s[2:3]
	s_waitcnt vmcnt(0)
	v_readfirstlane_b32 s2, v5
	s_nop 1
	v_add_u32_e32 v153, s2, v4
	v_mul_u32_u24_e32 v4, 0xaaab, v153
	v_lshrrev_b32_e32 v4, 17, v4
	v_mul_u32_u24_e32 v5, 3, v4
	v_sub_u32_e32 v5, v153, v5
	v_mul_u32_u24_e32 v4, 24, v4
	v_add3_u32 v153, v4, v5, s100
